# v024 + store-drain waits moved to the end of the accumulator re-zeroing blocks of all five GEMM K-loops
# baseline (speedup 1.0000x reference)
.LBB0_467:
	s_ashr_i32 s65, s64, 31
	s_lshl_b64 s[14:15], s[64:65], 19
	s_add_u32 s76, s19, s14
	s_addc_u32 s77, s42, s15
	s_and_b64 s[14:15], s[70:71], exec
	s_cselect_b32 s9, s77, s7
	s_cselect_b32 s13, s76, s6
	s_ashr_i32 s55, s54, 31
	s_lshl_b64 s[14:15], s[54:55], 19
	s_add_u32 s78, s43, s14
	s_addc_u32 s79, s46, s15
	s_and_b64 s[14:15], s[70:71], exec
	s_cselect_b32 s16, s79, s11
	s_cselect_b32 s17, s78, s10
	s_add_u32 s6, s6, 0x40080
	s_addc_u32 s7, s7, 0
	s_add_u32 s33, s10, 0x100
	v_mov_b32_e32 v34, 0
	s_addc_u32 s34, s11, 0
	s_mov_b32 s35, -2
	v_mov_b32_e32 v35, v34
	v_mov_b32_e32 v36, v34
	v_mov_b32_e32 v37, v34
	v_mov_b32_e32 v38, v34
	v_mov_b32_e32 v39, v34
	v_mov_b32_e32 v40, v34
	v_mov_b32_e32 v41, v34
	v_mov_b32_e32 v50, v34
	v_mov_b32_e32 v51, v34
	v_mov_b32_e32 v52, v34
	v_mov_b32_e32 v53, v34
	v_mov_b32_e32 v54, v34
	v_mov_b32_e32 v55, v34
	v_mov_b32_e32 v56, v34
	v_mov_b32_e32 v57, v34
	v_mov_b32_e32 v74, v34
	v_mov_b32_e32 v75, v34
	v_mov_b32_e32 v76, v34
	v_mov_b32_e32 v77, v34
	v_mov_b32_e32 v78, v34
	v_mov_b32_e32 v79, v34
	v_mov_b32_e32 v80, v34
	v_mov_b32_e32 v81, v34
	v_mov_b32_e32 v98, v34
	v_mov_b32_e32 v99, v34
	v_mov_b32_e32 v100, v34
	v_mov_b32_e32 v101, v34
	v_mov_b32_e32 v102, v34
	v_mov_b32_e32 v103, v34
	v_mov_b32_e32 v104, v34
	v_mov_b32_e32 v105, v34
	v_mov_b32_e32 v42, v34
	v_mov_b32_e32 v43, v34
	v_mov_b32_e32 v44, v34
	v_mov_b32_e32 v45, v34
	v_mov_b32_e32 v46, v34
	v_mov_b32_e32 v47, v34
	v_mov_b32_e32 v48, v34
	v_mov_b32_e32 v49, v34
	v_mov_b32_e32 v58, v34
	v_mov_b32_e32 v59, v34
	v_mov_b32_e32 v60, v34
	v_mov_b32_e32 v61, v34
	v_mov_b32_e32 v62, v34
	v_mov_b32_e32 v63, v34
	v_mov_b32_e32 v64, v34
	v_mov_b32_e32 v65, v34
	v_mov_b32_e32 v90, v34
	v_mov_b32_e32 v91, v34
	v_mov_b32_e32 v92, v34
	v_mov_b32_e32 v93, v34
	v_mov_b32_e32 v94, v34
	v_mov_b32_e32 v95, v34
	v_mov_b32_e32 v96, v34
	v_mov_b32_e32 v97, v34
	v_mov_b32_e32 v106, v34
	v_mov_b32_e32 v107, v34
	v_mov_b32_e32 v108, v34
	v_mov_b32_e32 v109, v34
	v_mov_b32_e32 v110, v34
	v_mov_b32_e32 v111, v34
	v_mov_b32_e32 v112, v34
	v_mov_b32_e32 v113, v34
	v_mov_b32_e32 v114, v34
	v_mov_b32_e32 v115, v34
	v_mov_b32_e32 v116, v34
	v_mov_b32_e32 v117, v34
	v_mov_b32_e32 v118, v34
	v_mov_b32_e32 v119, v34
	v_mov_b32_e32 v120, v34
	v_mov_b32_e32 v121, v34
	v_mov_b32_e32 v130, v34
	v_mov_b32_e32 v131, v34
	v_mov_b32_e32 v132, v34
	v_mov_b32_e32 v133, v34
	v_mov_b32_e32 v134, v34
	v_mov_b32_e32 v135, v34
	v_mov_b32_e32 v136, v34
	v_mov_b32_e32 v137, v34
	v_mov_b32_e32 v146, v34
	v_mov_b32_e32 v147, v34
	v_mov_b32_e32 v148, v34
	v_mov_b32_e32 v149, v34
	v_mov_b32_e32 v150, v34
	v_mov_b32_e32 v151, v34
	v_mov_b32_e32 v152, v34
	v_mov_b32_e32 v153, v34
	v_mov_b32_e32 v162, v34
	v_mov_b32_e32 v163, v34
	v_mov_b32_e32 v164, v34
	v_mov_b32_e32 v165, v34
	v_mov_b32_e32 v166, v34
	v_mov_b32_e32 v167, v34
	v_mov_b32_e32 v168, v34
	v_mov_b32_e32 v169, v34
	v_mov_b32_e32 v122, v34
	v_mov_b32_e32 v123, v34
	v_mov_b32_e32 v124, v34
	v_mov_b32_e32 v125, v34
	v_mov_b32_e32 v126, v34
	v_mov_b32_e32 v127, v34
	v_mov_b32_e32 v128, v34
	v_mov_b32_e32 v129, v34
	v_mov_b32_e32 v138, v34
	v_mov_b32_e32 v139, v34
	v_mov_b32_e32 v140, v34
	v_mov_b32_e32 v141, v34
	v_mov_b32_e32 v142, v34
	v_mov_b32_e32 v143, v34
	v_mov_b32_e32 v144, v34
	v_mov_b32_e32 v145, v34
	v_mov_b32_e32 v154, v34
	v_mov_b32_e32 v155, v34
	v_mov_b32_e32 v156, v34
	v_mov_b32_e32 v157, v34
	v_mov_b32_e32 v158, v34
	v_mov_b32_e32 v159, v34
	v_mov_b32_e32 v160, v34
	v_mov_b32_e32 v161, v34
	v_mov_b32_e32 v170, v34
	v_mov_b32_e32 v171, v34
	v_mov_b32_e32 v172, v34
	v_mov_b32_e32 v173, v34
	v_mov_b32_e32 v174, v34
	v_mov_b32_e32 v175, v34
	v_mov_b32_e32 v176, v34
	v_mov_b32_e32 v177, v34
	s_waitcnt vmcnt(0)

.LBB0_1095:
	s_ashr_i32 s21, s20, 31
	s_lshl_b64 s[24:25], s[20:21], 19
	s_add_u32 s24, s52, s24
	s_addc_u32 s25, s53, s25
	s_and_b64 s[26:27], s[22:23], exec
	s_cselect_b32 s21, s25, s5
	s_cselect_b32 s29, s24, s4
	s_ashr_i32 s19, s18, 31
	s_lshl_b64 s[26:27], s[18:19], 19
	s_add_u32 s26, s54, s26
	s_addc_u32 s27, s55, s27
	s_and_b64 s[34:35], s[22:23], exec
	s_cselect_b32 s19, s27, s51
	s_cselect_b32 s31, s26, s50
	s_add_u32 s4, s4, 0x40080
	s_addc_u32 s5, s5, 0
	s_add_u32 s33, s50, 0x100
	v_mov_b32_e32 v2, 0
	s_addc_u32 s34, s51, 0
	s_mov_b32 s35, -2
	v_mov_b32_e32 v3, v2
	v_mov_b32_e32 v4, v2
	v_mov_b32_e32 v5, v2
	v_mov_b32_e32 v6, v2
	v_mov_b32_e32 v7, v2
	v_mov_b32_e32 v8, v2
	v_mov_b32_e32 v9, v2
	v_mov_b32_e32 v18, v2
	v_mov_b32_e32 v19, v2
	v_mov_b32_e32 v20, v2
	v_mov_b32_e32 v21, v2
	v_mov_b32_e32 v22, v2
	v_mov_b32_e32 v23, v2
	v_mov_b32_e32 v24, v2
	v_mov_b32_e32 v25, v2
	v_mov_b32_e32 v34, v2
	v_mov_b32_e32 v35, v2
	v_mov_b32_e32 v36, v2
	v_mov_b32_e32 v37, v2
	v_mov_b32_e32 v38, v2
	v_mov_b32_e32 v39, v2
	v_mov_b32_e32 v40, v2
	v_mov_b32_e32 v41, v2
	v_mov_b32_e32 v66, v2
	v_mov_b32_e32 v67, v2
	v_mov_b32_e32 v68, v2
	v_mov_b32_e32 v69, v2
	v_mov_b32_e32 v78, v2
	v_mov_b32_e32 v79, v2
	v_mov_b32_e32 v80, v2
	v_mov_b32_e32 v81, v2
	v_mov_b32_e32 v10, v2
	v_mov_b32_e32 v11, v2
	v_mov_b32_e32 v12, v2
	v_mov_b32_e32 v13, v2
	v_mov_b32_e32 v14, v2
	v_mov_b32_e32 v15, v2
	v_mov_b32_e32 v16, v2
	v_mov_b32_e32 v17, v2
	v_mov_b32_e32 v26, v2
	v_mov_b32_e32 v27, v2
	v_mov_b32_e32 v28, v2
	v_mov_b32_e32 v29, v2
	v_mov_b32_e32 v30, v2
	v_mov_b32_e32 v31, v2
	v_mov_b32_e32 v32, v2
	v_mov_b32_e32 v33, v2
	v_mov_b32_e32 v42, v2
	v_mov_b32_e32 v43, v2
	v_mov_b32_e32 v44, v2
	v_mov_b32_e32 v45, v2
	v_mov_b32_e32 v46, v2
	v_mov_b32_e32 v47, v2
	v_mov_b32_e32 v48, v2
	v_mov_b32_e32 v49, v2
	v_mov_b32_e32 v82, v2
	v_mov_b32_e32 v83, v2
	v_mov_b32_e32 v84, v2
	v_mov_b32_e32 v85, v2
	v_mov_b32_e32 v86, v2
	v_mov_b32_e32 v87, v2
	v_mov_b32_e32 v88, v2
	v_mov_b32_e32 v89, v2
	v_mov_b32_e32 v98, v2
	v_mov_b32_e32 v99, v2
	v_mov_b32_e32 v100, v2
	v_mov_b32_e32 v101, v2
	v_mov_b32_e32 v102, v2
	v_mov_b32_e32 v103, v2
	v_mov_b32_e32 v104, v2
	v_mov_b32_e32 v105, v2
	v_mov_b32_e32 v114, v2
	v_mov_b32_e32 v115, v2
	v_mov_b32_e32 v116, v2
	v_mov_b32_e32 v117, v2
	v_mov_b32_e32 v118, v2
	v_mov_b32_e32 v119, v2
	v_mov_b32_e32 v120, v2
	v_mov_b32_e32 v121, v2
	v_mov_b32_e32 v130, v2
	v_mov_b32_e32 v131, v2
	v_mov_b32_e32 v132, v2
	v_mov_b32_e32 v133, v2
	v_mov_b32_e32 v134, v2
	v_mov_b32_e32 v135, v2
	v_mov_b32_e32 v136, v2
	v_mov_b32_e32 v137, v2
	v_mov_b32_e32 v146, v2
	v_mov_b32_e32 v147, v2
	v_mov_b32_e32 v148, v2
	v_mov_b32_e32 v149, v2
	v_mov_b32_e32 v150, v2
	v_mov_b32_e32 v151, v2
	v_mov_b32_e32 v152, v2
	v_mov_b32_e32 v153, v2
	v_mov_b32_e32 v106, v2
	v_mov_b32_e32 v107, v2
	v_mov_b32_e32 v108, v2
	v_mov_b32_e32 v109, v2
	v_mov_b32_e32 v110, v2
	v_mov_b32_e32 v111, v2
	v_mov_b32_e32 v112, v2
	v_mov_b32_e32 v113, v2
	v_mov_b32_e32 v122, v2
	v_mov_b32_e32 v123, v2
	v_mov_b32_e32 v124, v2
	v_mov_b32_e32 v125, v2
	v_mov_b32_e32 v126, v2
	v_mov_b32_e32 v127, v2
	v_mov_b32_e32 v128, v2
	v_mov_b32_e32 v129, v2
	v_mov_b32_e32 v138, v2
	v_mov_b32_e32 v139, v2
	v_mov_b32_e32 v140, v2
	v_mov_b32_e32 v141, v2
	v_mov_b32_e32 v142, v2
	v_mov_b32_e32 v143, v2
	v_mov_b32_e32 v144, v2
	v_mov_b32_e32 v145, v2
	v_mov_b32_e32 v154, v2
	v_mov_b32_e32 v155, v2
	v_mov_b32_e32 v156, v2
	v_mov_b32_e32 v157, v2
	v_mov_b32_e32 v158, v2
	v_mov_b32_e32 v159, v2
	v_mov_b32_e32 v160, v2
	v_mov_b32_e32 v161, v2
	s_waitcnt vmcnt(0)

.LBB0_1247:
	s_ashr_i32 s13, s12, 31
	s_lshl_b64 s[14:15], s[12:13], 19
	s_add_u32 s14, s26, s14
	s_addc_u32 s15, s27, s15
	s_and_b64 s[16:17], s[8:9], exec
	s_cselect_b32 s13, s15, s21
	s_cselect_b32 s19, s14, s20
	s_ashr_i32 s11, s10, 31
	s_lshl_b64 s[16:17], s[10:11], 19
	s_add_u32 s16, s28, s16
	s_addc_u32 s17, s29, s17
	s_and_b64 s[24:25], s[8:9], exec
	s_cselect_b32 s11, s17, s23
	s_cselect_b32 s44, s16, s22
	s_add_u32 s20, s20, 0x40080
	s_addc_u32 s21, s21, 0
	s_add_u32 s45, s22, 0x100
	v_mov_b32_e32 v2, 0
	s_addc_u32 s46, s23, 0
	s_mov_b32 s47, -2
	v_mov_b32_e32 v3, v2
	v_mov_b32_e32 v4, v2
	v_mov_b32_e32 v5, v2
	v_mov_b32_e32 v6, v2
	v_mov_b32_e32 v7, v2
	v_mov_b32_e32 v8, v2
	v_mov_b32_e32 v9, v2
	v_mov_b32_e32 v18, v2
	v_mov_b32_e32 v19, v2
	v_mov_b32_e32 v20, v2
	v_mov_b32_e32 v21, v2
	v_mov_b32_e32 v22, v2
	v_mov_b32_e32 v23, v2
	v_mov_b32_e32 v24, v2
	v_mov_b32_e32 v25, v2
	v_mov_b32_e32 v34, v2
	v_mov_b32_e32 v35, v2
	v_mov_b32_e32 v36, v2
	v_mov_b32_e32 v37, v2
	v_mov_b32_e32 v38, v2
	v_mov_b32_e32 v39, v2
	v_mov_b32_e32 v40, v2
	v_mov_b32_e32 v41, v2
	v_mov_b32_e32 v50, v2
	v_mov_b32_e32 v51, v2
	v_mov_b32_e32 v52, v2
	v_mov_b32_e32 v53, v2
	v_mov_b32_e32 v54, v2
	v_mov_b32_e32 v55, v2
	v_mov_b32_e32 v56, v2
	v_mov_b32_e32 v57, v2
	v_mov_b32_e32 v10, v2
	v_mov_b32_e32 v11, v2
	v_mov_b32_e32 v12, v2
	v_mov_b32_e32 v13, v2
	v_mov_b32_e32 v14, v2
	v_mov_b32_e32 v15, v2
	v_mov_b32_e32 v16, v2
	v_mov_b32_e32 v17, v2
	v_mov_b32_e32 v26, v2
	v_mov_b32_e32 v27, v2
	v_mov_b32_e32 v28, v2
	v_mov_b32_e32 v29, v2
	v_mov_b32_e32 v30, v2
	v_mov_b32_e32 v31, v2
	v_mov_b32_e32 v32, v2
	v_mov_b32_e32 v33, v2
	v_mov_b32_e32 v42, v2
	v_mov_b32_e32 v43, v2
	v_mov_b32_e32 v44, v2
	v_mov_b32_e32 v45, v2
	v_mov_b32_e32 v46, v2
	v_mov_b32_e32 v47, v2
	v_mov_b32_e32 v48, v2
	v_mov_b32_e32 v49, v2
	v_mov_b32_e32 v58, v2
	v_mov_b32_e32 v59, v2
	v_mov_b32_e32 v60, v2
	v_mov_b32_e32 v61, v2
	v_mov_b32_e32 v62, v2
	v_mov_b32_e32 v63, v2
	v_mov_b32_e32 v64, v2
	v_mov_b32_e32 v65, v2
	v_mov_b32_e32 v66, v2
	v_mov_b32_e32 v67, v2
	v_mov_b32_e32 v68, v2
	v_mov_b32_e32 v69, v2
	v_mov_b32_e32 v70, v2
	v_mov_b32_e32 v71, v2
	v_mov_b32_e32 v72, v2
	v_mov_b32_e32 v73, v2
	v_mov_b32_e32 v82, v2
	v_mov_b32_e32 v83, v2
	v_mov_b32_e32 v84, v2
	v_mov_b32_e32 v85, v2
	v_mov_b32_e32 v86, v2
	v_mov_b32_e32 v87, v2
	v_mov_b32_e32 v88, v2
	v_mov_b32_e32 v89, v2
	v_mov_b32_e32 v98, v2
	v_mov_b32_e32 v99, v2
	v_mov_b32_e32 v100, v2
	v_mov_b32_e32 v101, v2
	v_mov_b32_e32 v102, v2
	v_mov_b32_e32 v103, v2
	v_mov_b32_e32 v104, v2
	v_mov_b32_e32 v105, v2
	v_mov_b32_e32 v114, v2
	v_mov_b32_e32 v115, v2
	v_mov_b32_e32 v116, v2
	v_mov_b32_e32 v117, v2
	v_mov_b32_e32 v118, v2
	v_mov_b32_e32 v119, v2
	v_mov_b32_e32 v120, v2
	v_mov_b32_e32 v121, v2
	v_mov_b32_e32 v74, v2
	v_mov_b32_e32 v75, v2
	v_mov_b32_e32 v76, v2
	v_mov_b32_e32 v77, v2
	v_mov_b32_e32 v78, v2
	v_mov_b32_e32 v79, v2
	v_mov_b32_e32 v80, v2
	v_mov_b32_e32 v81, v2
	v_mov_b32_e32 v90, v2
	v_mov_b32_e32 v91, v2
	v_mov_b32_e32 v92, v2
	v_mov_b32_e32 v93, v2
	v_mov_b32_e32 v94, v2
	v_mov_b32_e32 v95, v2
	v_mov_b32_e32 v96, v2
	v_mov_b32_e32 v97, v2
	v_mov_b32_e32 v106, v2
	v_mov_b32_e32 v107, v2
	v_mov_b32_e32 v108, v2
	v_mov_b32_e32 v109, v2
	v_mov_b32_e32 v110, v2
	v_mov_b32_e32 v111, v2
	v_mov_b32_e32 v112, v2
	v_mov_b32_e32 v113, v2
	v_mov_b32_e32 v122, v2
	v_mov_b32_e32 v123, v2
	v_mov_b32_e32 v124, v2
	v_mov_b32_e32 v125, v2
	v_mov_b32_e32 v126, v2
	v_mov_b32_e32 v127, v2
	v_mov_b32_e32 v128, v2
	v_mov_b32_e32 v129, v2
	s_waitcnt vmcnt(0)

.LBB0_1324:
	s_ashr_i32 s31, s30, 31
	s_lshl_b64 s[10:11], s[30:31], 19
	s_add_u32 s42, s36, s10
	s_addc_u32 s43, s54, s11
	s_and_b64 s[10:11], s[40:41], exec
	s_cselect_b32 s12, s43, s7
	s_cselect_b32 s13, s42, s6
	s_ashr_i32 s39, s38, 31
	s_lshl_b64 s[10:11], s[38:39], 19
	s_add_u32 s44, s55, s10
	s_addc_u32 s45, s56, s11
	s_and_b64 s[10:11], s[40:41], exec
	s_cselect_b32 s14, s45, s9
	s_cselect_b32 s15, s44, s8
	s_add_u32 s6, s6, 0x40080
	s_addc_u32 s7, s7, 0
	s_add_u32 s31, s8, 0x100
	v_mov_b32_e32 v34, 0
	s_addc_u32 s35, s9, 0
	s_mov_b32 s39, -2
	v_mov_b32_e32 v35, v34
	v_mov_b32_e32 v36, v34
	v_mov_b32_e32 v37, v34
	v_mov_b32_e32 v38, v34
	v_mov_b32_e32 v39, v34
	v_mov_b32_e32 v40, v34
	v_mov_b32_e32 v41, v34
	v_mov_b32_e32 v50, v34
	v_mov_b32_e32 v51, v34
	v_mov_b32_e32 v52, v34
	v_mov_b32_e32 v53, v34
	v_mov_b32_e32 v54, v34
	v_mov_b32_e32 v55, v34
	v_mov_b32_e32 v56, v34
	v_mov_b32_e32 v57, v34
	v_mov_b32_e32 v74, v34
	v_mov_b32_e32 v75, v34
	v_mov_b32_e32 v76, v34
	v_mov_b32_e32 v77, v34
	v_mov_b32_e32 v78, v34
	v_mov_b32_e32 v79, v34
	v_mov_b32_e32 v80, v34
	v_mov_b32_e32 v81, v34
	v_mov_b32_e32 v98, v34
	v_mov_b32_e32 v99, v34
	v_mov_b32_e32 v100, v34
	v_mov_b32_e32 v101, v34
	v_mov_b32_e32 v102, v34
	v_mov_b32_e32 v103, v34
	v_mov_b32_e32 v104, v34
	v_mov_b32_e32 v105, v34
	v_mov_b32_e32 v42, v34
	v_mov_b32_e32 v43, v34
	v_mov_b32_e32 v44, v34
	v_mov_b32_e32 v45, v34
	v_mov_b32_e32 v46, v34
	v_mov_b32_e32 v47, v34
	v_mov_b32_e32 v48, v34
	v_mov_b32_e32 v49, v34
	v_mov_b32_e32 v58, v34
	v_mov_b32_e32 v59, v34
	v_mov_b32_e32 v60, v34
	v_mov_b32_e32 v61, v34
	v_mov_b32_e32 v62, v34
	v_mov_b32_e32 v63, v34
	v_mov_b32_e32 v64, v34
	v_mov_b32_e32 v65, v34
	v_mov_b32_e32 v90, v34
	v_mov_b32_e32 v91, v34
	v_mov_b32_e32 v92, v34
	v_mov_b32_e32 v93, v34
	v_mov_b32_e32 v94, v34
	v_mov_b32_e32 v95, v34
	v_mov_b32_e32 v96, v34
	v_mov_b32_e32 v97, v34
	v_mov_b32_e32 v106, v34
	v_mov_b32_e32 v107, v34
	v_mov_b32_e32 v108, v34
	v_mov_b32_e32 v109, v34
	v_mov_b32_e32 v110, v34
	v_mov_b32_e32 v111, v34
	v_mov_b32_e32 v112, v34
	v_mov_b32_e32 v113, v34
	v_mov_b32_e32 v114, v34
	v_mov_b32_e32 v115, v34
	v_mov_b32_e32 v116, v34
	v_mov_b32_e32 v117, v34
	v_mov_b32_e32 v118, v34
	v_mov_b32_e32 v119, v34
	v_mov_b32_e32 v120, v34
	v_mov_b32_e32 v121, v34
	v_mov_b32_e32 v130, v34
	v_mov_b32_e32 v131, v34
	v_mov_b32_e32 v132, v34
	v_mov_b32_e32 v133, v34
	v_mov_b32_e32 v134, v34
	v_mov_b32_e32 v135, v34
	v_mov_b32_e32 v136, v34
	v_mov_b32_e32 v137, v34
	v_mov_b32_e32 v146, v34
	v_mov_b32_e32 v147, v34
	v_mov_b32_e32 v148, v34
	v_mov_b32_e32 v149, v34
	v_mov_b32_e32 v150, v34
	v_mov_b32_e32 v151, v34
	v_mov_b32_e32 v152, v34
	v_mov_b32_e32 v153, v34
	v_mov_b32_e32 v162, v34
	v_mov_b32_e32 v163, v34
	v_mov_b32_e32 v164, v34
	v_mov_b32_e32 v165, v34
	v_mov_b32_e32 v166, v34
	v_mov_b32_e32 v167, v34
	v_mov_b32_e32 v168, v34
	v_mov_b32_e32 v169, v34
	v_mov_b32_e32 v122, v34
	v_mov_b32_e32 v123, v34
	v_mov_b32_e32 v124, v34
	v_mov_b32_e32 v125, v34
	v_mov_b32_e32 v126, v34
	v_mov_b32_e32 v127, v34
	v_mov_b32_e32 v128, v34
	v_mov_b32_e32 v129, v34
	v_mov_b32_e32 v138, v34
	v_mov_b32_e32 v139, v34
	v_mov_b32_e32 v140, v34
	v_mov_b32_e32 v141, v34
	v_mov_b32_e32 v142, v34
	v_mov_b32_e32 v143, v34
	v_mov_b32_e32 v144, v34
	v_mov_b32_e32 v145, v34
	v_mov_b32_e32 v154, v34
	v_mov_b32_e32 v155, v34
	v_mov_b32_e32 v156, v34
	v_mov_b32_e32 v157, v34
	v_mov_b32_e32 v158, v34
	v_mov_b32_e32 v159, v34
	v_mov_b32_e32 v160, v34
	v_mov_b32_e32 v161, v34
	v_mov_b32_e32 v170, v34
	v_mov_b32_e32 v171, v34
	v_mov_b32_e32 v172, v34
	v_mov_b32_e32 v173, v34
	v_mov_b32_e32 v174, v34
	v_mov_b32_e32 v175, v34
	v_mov_b32_e32 v176, v34
	v_mov_b32_e32 v177, v34
	s_waitcnt vmcnt(0)

.LBB0_1440:
	s_add_u32 s66, s30, 0x100
	v_mov_b32_e32 v2, 0
	s_addc_u32 s67, s31, 0
	s_mov_b32 s68, -2
	v_mov_b32_e32 v3, v2
	v_mov_b32_e32 v4, v2
	v_mov_b32_e32 v5, v2
	v_mov_b32_e32 v6, v2
	v_mov_b32_e32 v7, v2
	v_mov_b32_e32 v8, v2
	v_mov_b32_e32 v9, v2
	v_mov_b32_e32 v18, v2
	v_mov_b32_e32 v19, v2
	v_mov_b32_e32 v20, v2
	v_mov_b32_e32 v21, v2
	v_mov_b32_e32 v22, v2
	v_mov_b32_e32 v23, v2
	v_mov_b32_e32 v24, v2
	v_mov_b32_e32 v25, v2
	v_mov_b32_e32 v34, v2
	v_mov_b32_e32 v35, v2
	v_mov_b32_e32 v36, v2
	v_mov_b32_e32 v37, v2
	v_mov_b32_e32 v38, v2
	v_mov_b32_e32 v39, v2
	v_mov_b32_e32 v40, v2
	v_mov_b32_e32 v41, v2
	v_mov_b32_e32 v50, v2
	v_mov_b32_e32 v51, v2
	v_mov_b32_e32 v52, v2
	v_mov_b32_e32 v53, v2
	v_mov_b32_e32 v54, v2
	v_mov_b32_e32 v55, v2
	v_mov_b32_e32 v56, v2
	v_mov_b32_e32 v57, v2
	v_mov_b32_e32 v10, v2
	v_mov_b32_e32 v11, v2
	v_mov_b32_e32 v12, v2
	v_mov_b32_e32 v13, v2
	v_mov_b32_e32 v14, v2
	v_mov_b32_e32 v15, v2
	v_mov_b32_e32 v16, v2
	v_mov_b32_e32 v17, v2
	v_mov_b32_e32 v26, v2
	v_mov_b32_e32 v27, v2
	v_mov_b32_e32 v28, v2
	v_mov_b32_e32 v29, v2
	v_mov_b32_e32 v30, v2
	v_mov_b32_e32 v31, v2
	v_mov_b32_e32 v32, v2
	v_mov_b32_e32 v33, v2
	v_mov_b32_e32 v42, v2
	v_mov_b32_e32 v43, v2
	v_mov_b32_e32 v44, v2
	v_mov_b32_e32 v45, v2
	v_mov_b32_e32 v46, v2
	v_mov_b32_e32 v47, v2
	v_mov_b32_e32 v48, v2
	v_mov_b32_e32 v49, v2
	v_mov_b32_e32 v58, v2
	v_mov_b32_e32 v59, v2
	v_mov_b32_e32 v60, v2
	v_mov_b32_e32 v61, v2
	v_mov_b32_e32 v62, v2
	v_mov_b32_e32 v63, v2
	v_mov_b32_e32 v64, v2
	v_mov_b32_e32 v65, v2
	v_mov_b32_e32 v82, v2
	v_mov_b32_e32 v83, v2
	v_mov_b32_e32 v84, v2
	v_mov_b32_e32 v85, v2
	v_mov_b32_e32 v86, v2
	v_mov_b32_e32 v87, v2
	v_mov_b32_e32 v88, v2
	v_mov_b32_e32 v89, v2
	v_mov_b32_e32 v98, v2
	v_mov_b32_e32 v99, v2
	v_mov_b32_e32 v100, v2
	v_mov_b32_e32 v101, v2
	v_mov_b32_e32 v102, v2
	v_mov_b32_e32 v103, v2
	v_mov_b32_e32 v104, v2
	v_mov_b32_e32 v105, v2
	v_mov_b32_e32 v114, v2
	v_mov_b32_e32 v115, v2
	v_mov_b32_e32 v116, v2
	v_mov_b32_e32 v117, v2
	v_mov_b32_e32 v118, v2
	v_mov_b32_e32 v119, v2
	v_mov_b32_e32 v120, v2
	v_mov_b32_e32 v121, v2
	v_mov_b32_e32 v130, v2
	v_mov_b32_e32 v131, v2
	v_mov_b32_e32 v132, v2
	v_mov_b32_e32 v133, v2
	v_mov_b32_e32 v134, v2
	v_mov_b32_e32 v135, v2
	v_mov_b32_e32 v136, v2
	v_mov_b32_e32 v137, v2
	v_mov_b32_e32 v90, v2
	v_mov_b32_e32 v91, v2
	v_mov_b32_e32 v92, v2
	v_mov_b32_e32 v93, v2
	v_mov_b32_e32 v94, v2
	v_mov_b32_e32 v95, v2
	v_mov_b32_e32 v96, v2
	v_mov_b32_e32 v97, v2
	v_mov_b32_e32 v106, v2
	v_mov_b32_e32 v107, v2
	v_mov_b32_e32 v108, v2
	v_mov_b32_e32 v109, v2
	v_mov_b32_e32 v110, v2
	v_mov_b32_e32 v111, v2
	v_mov_b32_e32 v112, v2
	v_mov_b32_e32 v113, v2
	v_mov_b32_e32 v122, v2
	v_mov_b32_e32 v123, v2
	v_mov_b32_e32 v124, v2
	v_mov_b32_e32 v125, v2
	v_mov_b32_e32 v126, v2
	v_mov_b32_e32 v127, v2
	v_mov_b32_e32 v128, v2
	v_mov_b32_e32 v129, v2
	v_mov_b32_e32 v138, v2
	v_mov_b32_e32 v139, v2
	v_mov_b32_e32 v140, v2
	v_mov_b32_e32 v141, v2
	v_mov_b32_e32 v142, v2
	v_mov_b32_e32 v143, v2
	v_mov_b32_e32 v144, v2
	v_mov_b32_e32 v145, v2
	s_waitcnt vmcnt(0)
